# gMLP inner loop: both halves of the LN gain/bias loads requested together; attention: second K/V load batch requested before the first is consumed
# speedup vs baseline: 1.0066x; 1.0004x over previous
; #define LAS __attribute__((address_space(3)))
; __device__ __forceinline__ void attn_phase(const KAS Args& a, LAS unsigned char* lds, int i, const int tid_, const int bid, const int nblk) {
;     ...
;         { const int key = tid >> 1, hh = tid & 1; const bool valid = (n > 0) || (key >= 128); const size_t mk = m0 + key - 128;
;           u32x4 k0v = {0u, 0u, 0u, 0u}, k1v = k0v, k2v = k0v, k3v = k0v;
;           if (valid) { const bf16_t* kp = QKV + mk * QKVC + 1024 + kvh * 64 + 16 * hh; k0v = *(const u32x4*)(kp); k1v = *(const u32x4*)(kp + 8); k2v = *(const u32x4*)(kp + 32); k3v = *(const u32x4*)(kp + 40); }
;           LAS bf16_t* kd = Ks + key * 72 + 16 * hh;
;           *(LAS u32x4*)(kd) = k0v; *(LAS u32x4*)(kd + 8) = k1v; *(LAS u32x4*)(kd + 32) = k2v; *(LAS u32x4*)(kd + 40) = k3v;
;         }
;         { const int kp = (wave & 1) * 64 + lane, dq = wave >> 1; const bool valid = (n > 0) || (kp >= 64); const size_t mk = m0 + 2 * kp - 128;
;           u32x4 va0 = {0u, 0u, 0u, 0u}, va1 = va0, vb0 = va0, vb1 = va0;
;           if (valid) { const bf16_t* vp = QKV + mk * QKVC + 1280 + kvh * 64 + 16 * dq; va0 = *(const u32x4*)(vp); va1 = *(const u32x4*)(vp + 8); vb0 = *(const u32x4*)(vp + QKVC); vb1 = *(const u32x4*)(vp + QKVC + 8); }
;           LAS unsigned* vt32 = (LAS unsigned*)Vt;
;     ...
;           VT_ST(0, va0.x, vb0.x); VT_ST(2, va0.y, vb0.y); VT_ST(4, va0.z, vb0.z); VT_ST(6, va0.w, vb0.w);
;           VT_ST(8, va1.x, vb1.x); VT_ST(10, va1.y, vb1.y); VT_ST(12, va1.z, vb1.z); VT_ST(14, va1.w, vb1.w);
;     ...
;         }
;         __syncthreads();
;         const int g = wave >> 1, qh = kvh * 4 + g; const float sink = a.sinks[i * 16 + qh];
.LBB0_130:
	s_or_b64 exec, exec, s[18:19]
	s_or_b64 s[16:17], s[16:17], s[38:39]
	v_mov_b32_e32 v177, 0x48
	v_mov_b32_e32 v176, 5
	v_mov_b32_e32 v252, 0x50
	v_mov_b32_e32 v251, 0xb00000
	v_mov_b32_e32 v250, 0x2000
	v_mov_b32_e32 v249, 0x500000
	v_mov_b32_e32 v247, 0x400000
	v_mov_b32_e32 v244, 0x1600
	v_mov_b32_e32 v245, 1
	v_mov_b32_e32 v24, 0
	v_mov_b32_e32 v25, 0
	v_mov_b32_e32 v26, 0
	v_mov_b32_e32 v27, 0
	v_mov_b32_e32 v28, 0
	v_mov_b32_e32 v29, 0
	v_mov_b32_e32 v30, 0
	v_mov_b32_e32 v31, 0
	v_mov_b32_e32 v32, 0
	v_mov_b32_e32 v33, 0
	v_mov_b32_e32 v34, 0
	v_mov_b32_e32 v35, 0
	v_mov_b32_e32 v36, 0
	v_mov_b32_e32 v37, 0
	v_mov_b32_e32 v38, 0
	v_mov_b32_e32 v39, 0
	s_andn2_b64 vcc, exec, s[16:17]
	s_cbranch_vccnz .Latt_nob2
	v_lshl_add_u64 v[0:1], s[44:45], 0, v[162:163]
	v_mov_b64_e32 v[40:41], s[80:81]
	v_mad_u64_u32 v[40:41], s[16:17], v0, s76, v[40:41]
	v_mov_b32_e32 v0, v41
	v_mad_u64_u32 v[0:1], s[16:17], v1, s76, v[0:1]
	v_mov_b32_e32 v41, v0
	s_lshl_b32 s92, s20, 7
	v_lshl_add_u64 v[0:1], v[40:41], 0, s[92:93]
	s_mov_b32 s16, 0xfffa0a00
	v_lshl_add_u64 v[0:1], s[40:41], 1, v[0:1]
	s_mov_b32 s17, -1
	v_lshl_add_u64 v[42:43], v[0:1], 0, s[16:17]
	s_mov_b32 s16, 0xfffa1000
	v_add_co_u32_e32 v0, vcc, s16, v0
	s_nop 1
	v_addc_co_u32_e32 v1, vcc, -1, v1, vcc
	global_load_dwordx4 v[24:27], v[0:1], off offset:-1536
	global_load_dwordx4 v[28:31], v[42:43], off offset:3088
	global_load_dwordx4 v[32:35], v[42:43], off offset:16
	s_nop 0
	global_load_dwordx4 v[36:39], v[42:43], off offset:3072
	s_waitcnt vmcnt(7)
	ds_write_b128 v202, v[10:13]
	s_waitcnt vmcnt(5)
	ds_write_b128 v202, v[18:21] offset:16
	s_waitcnt vmcnt(4)
	ds_write_b128 v202, v[14:17] offset:64
	ds_write_b128 v202, v[6:9] offset:80
	s_branch .LBB0_132
.Latt_nob2:
	s_waitcnt vmcnt(3)
	ds_write_b128 v202, v[10:13]
	s_waitcnt vmcnt(1)
	ds_write_b128 v202, v[18:21] offset:16
	s_waitcnt vmcnt(0)
	ds_write_b128 v202, v[14:17] offset:64
	ds_write_b128 v202, v[6:9] offset:80
.LBB0_132:
	s_waitcnt vmcnt(0)
	v_lshlrev_b32_e32 v0, 16, v36
	v_and_or_b32 v0, v24, s77, v0
	ds_write_b32 v175, v0 offset:36864
	v_lshrrev_b32_e32 v0, 16, v24
	s_mov_b32 s16, 0xffff0000
	v_and_or_b32 v0, v36, s16, v0
	v_add_u32_e32 v1, 0x210, v175
	ds_write_b32 v1, v0 offset:36864
	v_lshlrev_b32_e32 v0, 16, v37
	v_and_or_b32 v0, v25, s77, v0
	v_add_u32_e32 v1, 0x420, v175
	ds_write_b32 v1, v0 offset:36864
	v_lshrrev_b32_e32 v0, 16, v25
	v_and_or_b32 v0, v37, s16, v0
	ds_write_b32 v178, v0 offset:36864
	v_lshlrev_b32_e32 v0, 16, v38
	v_and_or_b32 v0, v26, s77, v0
	ds_write_b32 v179, v0 offset:36864
	v_lshrrev_b32_e32 v0, 16, v26
	v_and_or_b32 v0, v38, s16, v0
	ds_write_b32 v187, v0 offset:36864
	v_lshlrev_b32_e32 v0, 16, v39
	v_and_or_b32 v0, v27, s77, v0
	ds_write_b32 v188, v0 offset:36864
	v_lshrrev_b32_e32 v0, 16, v27
	v_and_or_b32 v0, v39, s16, v0
	ds_write_b32 v189, v0 offset:36864
	v_lshlrev_b32_e32 v0, 16, v28
	v_and_or_b32 v0, v32, s77, v0
	ds_write_b32 v190, v0 offset:36864
	v_lshrrev_b32_e32 v0, 16, v32
	v_and_or_b32 v0, v28, s16, v0
	ds_write_b32 v191, v0 offset:36864
	v_lshlrev_b32_e32 v0, 16, v29
	v_and_or_b32 v0, v33, s77, v0
	ds_write_b32 v192, v0 offset:36864
	v_lshrrev_b32_e32 v0, 16, v33
	v_and_or_b32 v0, v29, s16, v0
	ds_write_b32 v193, v0 offset:36864
	v_lshlrev_b32_e32 v0, 16, v30
	v_and_or_b32 v0, v34, s77, v0
	ds_write_b32 v194, v0 offset:36864
	v_lshrrev_b32_e32 v0, 16, v34
	v_and_or_b32 v0, v30, s16, v0
	ds_write_b32 v195, v0 offset:36864
	v_lshlrev_b32_e32 v0, 16, v31
	v_and_or_b32 v0, v35, s77, v0
	ds_write_b32 v196, v0 offset:36864
	v_lshrrev_b32_e32 v0, 16, v35
	v_and_or_b32 v0, v31, s16, v0
	s_lshl_b32 s16, s20, 2
	s_add_i32 s18, s16, s3
	s_add_i32 s16, s18, s48
	s_ashr_i32 s17, s16, 31
	s_lshl_b64 s[16:17], s[16:17], 2
	s_add_u32 s16, s36, s16
	s_addc_u32 s17, s37, s17
	ds_write_b32 v197, v0 offset:36864
	s_waitcnt lgkmcnt(0)
	s_barrier
	global_load_dword v169, v3, s[16:17]
	s_lshl_b32 s16, s18, 6
	s_ashr_i32 s17, s16, 31
	s_lshl_b64 s[18:19], s[16:17], 1
	s_cmp_eq_u32 s50, 0
	s_cselect_b64 s[16:17], -1, 0
	v_lshl_add_u64 v[170:171], v[164:165], 0, s[18:19]
	s_mov_b32 s52, 0
	v_lshl_add_u64 v[172:173], v[166:167], 0, s[18:19]
	s_or_b64 s[18:19], s[16:17], s[10:11]
	s_and_b64 s[20:21], s[16:17], s[42:43]
	s_mov_b64 s[46:47], -1
	s_mov_b32 s53, 0xff800000

; __device__ __forceinline__ unsigned pk2(float lo, float hi) { f32x2 v = {lo, hi}; bf16x2_t b = __builtin_convertvector(v, bf16x2_t); return __builtin_bit_cast(unsigned, b); }
; __device__ __forceinline__ void unpack8(const u32x4 w, float (&f)[8]) { f[0] = bflo(w.x); f[1] = bfhi(w.x); f[2] = bflo(w.y); f[3] = bfhi(w.y); f[4] = bflo(w.z); f[5] = bfhi(w.z); f[6] = bflo(w.w); f[7] = bfhi(w.w); }
; __device__ __forceinline__ void post_phase(const KAS Args& a, LAS unsigned char* lds, int i, const int tid_, const int bid, const int nblk) {
;     ...
;             { const float mean = stat[2 * stok], rstd = stat[2 * stok + 1];
; #pragma unroll
;               for (int q = 0; q < 4; ++q) { float sv[8], wv[8]; const int d0 = 32 * spart + 8 * q;
;                   unpack8(raw[q], sv);
; #pragma unroll
;                   for (int e = 0; e < 8; ++e) { const int dd = g * 128 + d0 + e; const float sn = (sv[e] - mean) * rstd * a.lng[i * 512 + dd] + a.lnb[i * 512 + dd];
;                       St[(d0 + e) * 136 + stok] = (bf16_t)(pk2(sn, 0.f) & 0xffffu); }
.LBB0_165:
	s_barrier
	ds_read2_b32 v[108:109], v90 offset1:1
	s_lshl_b32 s3, s2, 7
	s_add_i32 s76, s3, s95
	v_or_b32_e32 v2, s76, v86
	s_waitcnt vmcnt(11)
	v_lshlrev_b32_e32 v52, 16, v12
	v_lshlrev_b64 v[56:57], 2, v[2:3]
	s_waitcnt lgkmcnt(0)
	v_sub_f32_e32 v52, v52, v108
	v_lshl_add_u64 v[58:59], s[80:81], 0, v[56:57]
	v_lshl_add_u64 v[80:81], s[82:83], 0, v[56:57]
	v_lshl_add_u64 v[192:193], s[80:81], 0, v[56:57]
	v_lshl_add_u64 v[194:195], s[82:83], 0, v[56:57]
	v_mul_f32_e32 v117, v109, v52
	global_load_dwordx4 v[52:55], v[58:59], off offset:48
	global_load_dwordx4 v[60:63], v[58:59], off offset:32
	global_load_dwordx4 v[68:71], v[58:59], off offset:16
	global_load_dwordx4 v[72:75], v[58:59], off
	s_nop 0
	global_load_dwordx4 v[56:59], v[80:81], off offset:48
	global_load_dwordx4 v[64:67], v[80:81], off offset:32
	global_load_dwordx4 v[76:79], v[80:81], off offset:16
	s_nop 0
	global_load_dwordx4 v[80:83], v[80:81], off
	global_load_dwordx4 v[150:153], v[192:193], off offset:112
	global_load_dwordx4 v[154:157], v[192:193], off offset:96
	global_load_dwordx4 v[158:161], v[192:193], off offset:80
	global_load_dwordx4 v[162:165], v[192:193], off offset:64
	global_load_dwordx4 v[166:169], v[194:195], off offset:112
	global_load_dwordx4 v[170:173], v[194:195], off offset:96
	global_load_dwordx4 v[174:177], v[194:195], off offset:80
	global_load_dwordx4 v[188:191], v[194:195], off offset:64
	v_and_b32_e32 v110, 0xffff0000, v12
	v_lshlrev_b32_e32 v111, 16, v13
	v_and_b32_e32 v112, 0xffff0000, v13
	v_lshlrev_b32_e32 v113, 16, v14
	v_and_b32_e32 v114, 0xffff0000, v14
	v_lshlrev_b32_e32 v115, 16, v15
	v_and_b32_e32 v116, 0xffff0000, v15
	s_cmp_eq_u32 s2, 3
	s_waitcnt vmcnt(8)
	v_fma_f32 v2, v117, v72, v80
	v_cvt_pk_bf16_f32 v2, v2, s0
	ds_write_b16 v130, v2 offset:35840
	v_sub_f32_e32 v2, v110, v108
	v_mul_f32_e32 v2, v109, v2
	v_fma_f32 v2, v2, v73, v81
	v_cvt_pk_bf16_f32 v2, v2, s0
	ds_write_b16 v130, v2 offset:36112
	v_sub_f32_e32 v2, v111, v108
	v_mul_f32_e32 v2, v109, v2
	v_fma_f32 v2, v2, v74, v82
	v_cvt_pk_bf16_f32 v2, v2, s0
	ds_write_b16 v130, v2 offset:36384
	v_sub_f32_e32 v2, v112, v108
	v_mul_f32_e32 v2, v109, v2
	v_fmac_f32_e32 v83, v2, v75
	v_cvt_pk_bf16_f32 v2, v83, s0
	ds_write_b16 v130, v2 offset:36656
	v_sub_f32_e32 v2, v113, v108
	v_mul_f32_e32 v2, v109, v2
	v_fma_f32 v2, v2, v68, v76
	v_cvt_pk_bf16_f32 v2, v2, s0
	ds_write_b16 v130, v2 offset:36928
	v_sub_f32_e32 v2, v114, v108
	v_mul_f32_e32 v2, v109, v2
	v_fma_f32 v2, v2, v69, v77
	v_cvt_pk_bf16_f32 v2, v2, s0
	ds_write_b16 v130, v2 offset:37200
	v_sub_f32_e32 v2, v115, v108
	v_mul_f32_e32 v2, v109, v2
	v_fma_f32 v2, v2, v70, v78
	v_cvt_pk_bf16_f32 v2, v2, s0
	ds_write_b16 v130, v2 offset:37472
	v_sub_f32_e32 v2, v116, v108
	v_mul_f32_e32 v2, v109, v2
	v_fmac_f32_e32 v79, v2, v71
	v_cvt_pk_bf16_f32 v2, v79, s0
	ds_write_b16 v130, v2 offset:37744
	v_cndmask_b32_e64 v2, v32, 0, s[8:9]
	v_cndmask_b32_e64 v68, 0, v33, s[12:13]
	v_cvt_pk_bf16_f32 v68, v2, v68
	v_lshlrev_b32_e32 v2, 16, v16
	v_cndmask_b32_e64 v70, v28, 0, s[10:11]
	v_cndmask_b32_e64 v71, v29, 0, s[14:15]
	v_cndmask_b32_e64 v69, v34, 0, s[16:17]
	v_cndmask_b32_e64 v72, v30, 0, s[18:19]
	v_cndmask_b32_e64 v73, v35, 0, s[20:21]
	v_cndmask_b32_e64 v74, v31, 0, s[22:23]
	v_sub_f32_e32 v2, v2, v108
	v_cvt_pk_bf16_f32 v69, v69, v73
	v_cvt_pk_bf16_f32 v70, v70, v71
	v_cvt_pk_bf16_f32 v71, v72, v74
	v_mul_f32_e32 v79, v109, v2
	v_add_u32_e32 v2, s76, v86
	ds_write_b128 v95, v[68:71] offset:1024
	v_lshlrev_b64 v[70:71], 2, v[2:3]
	v_fma_f32 v2, v79, v60, v64
	v_and_b32_e32 v72, 0xffff0000, v16
	v_cvt_pk_bf16_f32 v2, v2, s0
	ds_write_b16 v130, v2 offset:38016
	v_sub_f32_e32 v2, v72, v108
	v_mul_f32_e32 v2, v109, v2
	v_fma_f32 v2, v2, v61, v65
	v_lshlrev_b32_e32 v73, 16, v17
	v_cvt_pk_bf16_f32 v2, v2, s0
	ds_write_b16 v130, v2 offset:38288
	v_sub_f32_e32 v2, v73, v108
	v_mul_f32_e32 v2, v109, v2
	v_fma_f32 v2, v2, v62, v66
	v_and_b32_e32 v74, 0xffff0000, v17
	v_cvt_pk_bf16_f32 v2, v2, s0
	ds_write_b16 v130, v2 offset:38560
	v_sub_f32_e32 v2, v74, v108
	v_mul_f32_e32 v2, v109, v2
	v_fmac_f32_e32 v67, v2, v63
	v_lshlrev_b32_e32 v75, 16, v18
	v_cvt_pk_bf16_f32 v2, v67, s0
	ds_write_b16 v130, v2 offset:38832
	v_sub_f32_e32 v2, v75, v108
	v_mul_f32_e32 v2, v109, v2
	v_fma_f32 v2, v2, v52, v56
	v_and_b32_e32 v76, 0xffff0000, v18
	v_cvt_pk_bf16_f32 v2, v2, s0
	ds_write_b16 v130, v2 offset:39104
	v_sub_f32_e32 v2, v76, v108
	v_mul_f32_e32 v2, v109, v2
	v_fma_f32 v2, v2, v53, v57
	v_lshlrev_b32_e32 v77, 16, v19
	v_cvt_pk_bf16_f32 v2, v2, s0
	ds_write_b16 v130, v2 offset:39376
	v_sub_f32_e32 v2, v77, v108
	v_mul_f32_e32 v2, v109, v2
	v_fma_f32 v2, v2, v54, v58
	v_and_b32_e32 v78, 0xffff0000, v19
	v_cvt_pk_bf16_f32 v2, v2, s0
	ds_write_b16 v130, v2 offset:39648
	v_sub_f32_e32 v2, v78, v108
	v_mul_f32_e32 v2, v109, v2
	v_fmac_f32_e32 v59, v2, v55
	v_cvt_pk_bf16_f32 v2, v59, s0
	ds_write_b16 v130, v2 offset:39920
	v_cndmask_b32_e64 v2, v24, 0, s[24:25]
	v_cndmask_b32_e64 v54, v20, 0, s[26:27]
	v_cndmask_b32_e64 v52, v25, 0, s[28:29]
	v_cndmask_b32_e64 v55, v21, 0, s[30:31]
	v_cndmask_b32_e64 v53, v26, 0, s[34:35]
	v_cndmask_b32_e64 v56, v22, 0, s[36:37]
	v_cndmask_b32_e64 v57, v27, 0, s[38:39]
	v_cndmask_b32_e64 v58, v23, 0, s[40:41]
	v_cvt_pk_bf16_f32 v52, v2, v52
	v_cvt_pk_bf16_f32 v53, v53, v57
	v_cvt_pk_bf16_f32 v54, v54, v55
	v_cvt_pk_bf16_f32 v55, v56, v58
	ds_write_b128 v95, v[52:55] offset:1040
	v_lshlrev_b32_e32 v52, 16, v8
	v_sub_f32_e32 v52, v52, v108
	v_mul_f32_e32 v116, v109, v52
	s_nop 0
	s_nop 0
	v_and_b32_e32 v115, 0xffff0000, v8
	v_lshlrev_b32_e32 v114, 16, v9
	v_and_b32_e32 v113, 0xffff0000, v9
	v_lshlrev_b32_e32 v112, 16, v10
	v_and_b32_e32 v111, 0xffff0000, v10
	v_lshlrev_b32_e32 v110, 16, v11
	v_and_b32_e32 v2, 0xffff0000, v11
	v_sub_f32_e32 v2, v2, v108
	v_mul_f32_e32 v2, v109, v2
	s_mov_b32 s76, 4
	s_waitcnt vmcnt(0)
; __device__ __forceinline__ unsigned pk2(float lo, float hi) { f32x2 v = {lo, hi}; bf16x2_t b = __builtin_convertvector(v, bf16x2_t); return __builtin_bit_cast(unsigned, b); }
; #define LAS __attribute__((address_space(3)))
; __device__ __forceinline__ void unpack8(const u32x4 w, float (&f)[8]) { f[0] = bflo(w.x); f[1] = bfhi(w.x); f[2] = bflo(w.y); f[3] = bfhi(w.y); f[4] = bflo(w.z); f[5] = bfhi(w.z); f[6] = bflo(w.w); f[7] = bfhi(w.w); }
; __device__ __forceinline__ u32x4 pack8(const float (&f)[8]) { return (u32x4){pk2(f[0], f[1]), pk2(f[2], f[3]), pk2(f[4], f[5]), pk2(f[6], f[7])}; }
; #define GM_LOAD(G) do { const float* wsrc_ = a.wsp + ((size_t)(i * 4 + (G)) * 128 + stok) * 128 + 32 * spart; _Pragma("unroll") for (int q = 0; q < 4; ++q) { \
;         raw[q] = *(const u32x4*)(Z + (m0 + stok) * ZC + 2304 + (G) * 128 + 32 * spart + 8 * q); wr0[q] = *(const f32x4*)(wsrc_ + 8 * q); wr1[q] = *(const f32x4*)(wsrc_ + 8 * q + 4); } } while (0)
; __device__ __forceinline__ void post_phase(const KAS Args& a, LAS unsigned char* lds, int i, const int tid_, const int bid, const int nblk) {
;     ...
;               for (int q = 0; q < 4; ++q) { float sv[8], wv[8]; const int d0 = 32 * spart + 8 * q;
;                   unpack8(raw[q], sv);
; #pragma unroll
;                   for (int e = 0; e < 8; ++e) { const int dd = g * 128 + d0 + e; const float sn = (sv[e] - mean) * rstd * a.lng[i * 512 + dd] + a.lnb[i * 512 + dd];
;                       St[(d0 + e) * 136 + stok] = (bf16_t)(pk2(sn, 0.f) & 0xffffu); }
; #pragma unroll
;                   for (int e = 0; e < 4; ++e) { wv[e] = (d0 + e <= stok) ? wr0[q][e] : 0.f; wv[4 + e] = (d0 + 4 + e <= stok) ? wr1[q][e] : 0.f; }
;                   *(LAS u32x4*)(Wl + stok * 136 + d0) = pack8(wv); } }
;             if (g < 3) GM_LOAD(g + 1);
	v_fmac_f32_e32 v177, v2, v161
	v_fma_f32 v162, v116, v162, v188
	v_cvt_pk_bf16_f32 v162, v162, s0
	ds_write_b16 v130, v162 offset:40192
	v_sub_f32_e32 v162, v115, v108
	v_mul_f32_e32 v162, v109, v162
	v_fma_f32 v162, v162, v163, v189
	v_cvt_pk_bf16_f32 v162, v162, s0
	ds_write_b16 v130, v162 offset:40464
	v_sub_f32_e32 v162, v114, v108
	v_mul_f32_e32 v162, v109, v162
	v_fma_f32 v162, v162, v164, v190
	v_cvt_pk_bf16_f32 v162, v162, s0
	ds_write_b16 v130, v162 offset:40736
	v_sub_f32_e32 v162, v113, v108
	v_mul_f32_e32 v162, v109, v162
	v_fmac_f32_e32 v191, v162, v165
	v_cvt_pk_bf16_f32 v162, v191, s0
	ds_write_b16 v130, v162 offset:41008
	v_sub_f32_e32 v162, v112, v108
	v_mul_f32_e32 v162, v109, v162
	v_fma_f32 v158, v162, v158, v174
	v_cvt_pk_bf16_f32 v158, v158, s0
	ds_write_b16 v130, v158 offset:41280
	v_sub_f32_e32 v158, v111, v108
	v_mul_f32_e32 v158, v109, v158
	v_fma_f32 v158, v158, v159, v175
	v_cvt_pk_bf16_f32 v158, v158, s0
	ds_write_b16 v130, v158 offset:41552
	v_sub_f32_e32 v158, v110, v108
	v_mul_f32_e32 v158, v109, v158
	v_fma_f32 v158, v158, v160, v176
	v_cvt_pk_bf16_f32 v158, v158, s0
	v_cvt_pk_bf16_f32 v2, v177, s0
	ds_write_b16 v130, v158 offset:41824
	ds_write_b16 v130, v2 offset:42096
	v_cndmask_b32_e64 v2, v48, 0, s[42:43]
	v_cndmask_b32_e64 v158, v49, 0, s[46:47]
	v_cvt_pk_bf16_f32 v158, v2, v158
	v_lshlrev_b32_e32 v2, 16, v4
	v_sub_f32_e32 v2, v2, v108
	v_cndmask_b32_e64 v160, v44, 0, s[44:45]
	v_cndmask_b32_e64 v161, v45, 0, s[48:49]
	v_cndmask_b32_e64 v159, v50, 0, s[50:51]
	v_cndmask_b32_e64 v174, v46, 0, s[52:53]
	v_cndmask_b32_e64 v175, v51, 0, s[54:55]
	v_cndmask_b32_e64 v176, v47, 0, s[56:57]
	v_mul_f32_e32 v2, v109, v2
	v_cvt_pk_bf16_f32 v159, v159, v175
	v_cvt_pk_bf16_f32 v160, v160, v161
	v_cvt_pk_bf16_f32 v161, v174, v176
	v_fma_f32 v2, v2, v154, v170
	ds_write_b128 v95, v[158:161] offset:1056
	v_and_b32_e32 v158, 0xffff0000, v4
	v_cvt_pk_bf16_f32 v2, v2, s0
	ds_write_b16 v130, v2 offset:42368
	v_sub_f32_e32 v2, v158, v108
	v_mul_f32_e32 v2, v109, v2
	v_fma_f32 v2, v2, v155, v171
	v_lshlrev_b32_e32 v159, 16, v5
	v_cvt_pk_bf16_f32 v2, v2, s0
	ds_write_b16 v130, v2 offset:42640
	v_sub_f32_e32 v2, v159, v108
	v_mul_f32_e32 v2, v109, v2
	v_fma_f32 v2, v2, v156, v172
	v_and_b32_e32 v160, 0xffff0000, v5
	v_cvt_pk_bf16_f32 v2, v2, s0
	ds_write_b16 v130, v2 offset:42912
	v_sub_f32_e32 v2, v160, v108
	v_mul_f32_e32 v2, v109, v2
	v_fmac_f32_e32 v173, v2, v157
	v_lshlrev_b32_e32 v161, 16, v6
	v_cvt_pk_bf16_f32 v2, v173, s0
	ds_write_b16 v130, v2 offset:43184
	v_sub_f32_e32 v2, v161, v108
	v_mul_f32_e32 v2, v109, v2
	v_fma_f32 v2, v2, v150, v166
	v_and_b32_e32 v174, 0xffff0000, v6
	v_cvt_pk_bf16_f32 v2, v2, s0
	ds_write_b16 v130, v2 offset:43456
	v_sub_f32_e32 v2, v174, v108
	v_mul_f32_e32 v2, v109, v2
	v_fma_f32 v2, v2, v151, v167
	v_lshlrev_b32_e32 v175, 16, v7
	v_cvt_pk_bf16_f32 v2, v2, s0
	ds_write_b16 v130, v2 offset:43728
	v_sub_f32_e32 v2, v175, v108
	v_mul_f32_e32 v2, v109, v2
	v_fma_f32 v2, v2, v152, v168
	v_and_b32_e32 v176, 0xffff0000, v7
	v_cvt_pk_bf16_f32 v2, v2, s0
	ds_write_b16 v130, v2 offset:44000
	v_sub_f32_e32 v2, v176, v108
	v_mul_f32_e32 v2, v109, v2
	v_fmac_f32_e32 v169, v2, v153
	v_cvt_pk_bf16_f32 v2, v169, s0
	ds_write_b16 v130, v2 offset:44272
	v_cndmask_b32_e64 v2, v40, 0, s[58:59]
	v_cndmask_b32_e64 v152, v36, 0, s[60:61]
	v_cndmask_b32_e64 v150, v41, 0, s[62:63]
	v_cndmask_b32_e64 v153, v37, 0, s[64:65]
	v_cndmask_b32_e64 v151, v42, 0, s[66:67]
	v_cndmask_b32_e64 v154, v38, 0, s[68:69]
	v_cndmask_b32_e64 v155, v43, 0, s[70:71]
	v_cndmask_b32_e64 v156, v39, 0, s[72:73]
	v_cvt_pk_bf16_f32 v150, v2, v150
	v_cvt_pk_bf16_f32 v151, v151, v155
	v_cvt_pk_bf16_f32 v152, v152, v153
	v_cvt_pk_bf16_f32 v153, v154, v156
	ds_write_b128 v95, v[150:153] offset:1072
	s_cbranch_scc1 .LBB0_164
	s_add_i32 s76, s2, 1
	s_add_i32 s92, s76, s74
	s_lshl_b64 vcc, s[92:93], 16
	s_lshl_b32 s92, s76, 8
	v_lshl_add_u64 v[48:49], v[92:93], 0, vcc
	v_lshl_add_u64 v[12:13], v[102:103], 0, s[92:93]
	global_load_dwordx4 v[4:7], v[12:13], off offset:48
	global_load_dwordx4 v[8:11], v[12:13], off offset:32
	global_load_dwordx4 v[16:19], v[12:13], off offset:16
	s_nop 0
	global_load_dwordx4 v[12:15], v[12:13], off
	s_nop 0
	global_load_dwordx4 v[20:23], v[48:49], off offset:48
	global_load_dwordx4 v[24:27], v[48:49], off offset:32
	global_load_dwordx4 v[28:31], v[48:49], off offset:16
	global_load_dwordx4 v[32:35], v[48:49], off
	global_load_dwordx4 v[36:39], v[48:49], off offset:112
	global_load_dwordx4 v[40:43], v[48:49], off offset:96
	global_load_dwordx4 v[44:47], v[48:49], off offset:80
	s_nop 0
	global_load_dwordx4 v[48:51], v[48:49], off offset:64
	s_branch .LBB0_164
